# combination variant (merged scan waits, gate ticket prefetch, barrier reorder, streaming weight conversion) plus 64 B loop-head alignment
# speedup vs baseline: 1.0013x; 1.0013x over previous
; __device__ __forceinline__ int tidx() { int t = threadIdx.x; asm volatile("" : "+v"(t)); return t; }
; template <int NT>
; __device__ __forceinline__ void gemm_tile(f32x4 (&acc)[4][NT], const bf16_t* A, int lda, const bf16_t* B, int ldb, int K, bf16_t* sm) {
;     const int tid_ = tidx();
;     bf16_t* sA = sm; bf16_t* sB = sm + 128 * LDT;
;     const int tid = tid_, lane = tid & 63, wid = tid >> 6, wr = wid >> 1, wc = wid & 1;
;     const int fr = lane & 15, fq = lane >> 4;
;     const int lrow = tid >> 3, lkc = tid & 7;
;     const bf16_t* ga = A + (size_t)lrow * lda + lkc * 8;
;     const bf16_t* gb = B + (size_t)lrow * ldb + lkc * 8;
;     int sbrow[NT];
; #pragma unroll
;     for (int i = 0; i < NT; ++i) { const int g = lrow + 32 * i, W_ = 16 * NT, rem = g % W_; sbrow[i] = (g / W_) * W_ + (rem % NT) * 16 + rem / NT; }
;     u32x4 ra0[4], rb0[NT];
; #pragma unroll
;     for (int i = 0; i < 4; ++i) ra0[i] = *(const u32x4*)(ga + (size_t)(32 * i) * lda);
; #pragma unroll
;     for (int i = 0; i < NT; ++i) rb0[i] = *(const u32x4*)(gb + (size_t)(32 * i) * ldb);
;     const int nk = K >> 6;
; __device__ __forceinline__ void gate_tile(int t, const bf16_t* xb, const bf16_t* Wg, bf16_t* G, bf16_t* sm) {
;     const int tid_ = tidx();
;     const int lane = tid_ & 63, wid = tid_ >> 6, wr = wid >> 1, wc = wid & 1, fr = lane & 15, fq = lane >> 4;
;     const int tm = t >> 5, tn = t & 31;
;     f32x4 acc[4][4]; zero_acc<4>(acc);
;     gemm_tile<4>(acc, xb + (size_t)tm * 128 * 1024, 1024, Wg + (size_t)tn * 128 * 1024, 1024, 1024, sm);
.Lq_pf_skip:
	s_or_b64 exec, exec, s[14:15]
	s_mov_b32 s14, 1
	v_writelane_b32 v234, s14, 9
	v_mov_b32_e32 v12, v192
	v_mov_b32_e32 v40, v192
	s_add_i32 s2, s74, 0xfffffa80
	v_ashrrev_i32_e32 v0, 31, v40
	s_waitcnt vmcnt(6)
	v_ashrrev_i32_e32 v30, 3, v40
	v_lshrrev_b32_e32 v0, 26, v0
	v_add_u32_e32 v0, v30, v0
	v_lshrrev_b32_e32 v1, 6, v0
	v_mul_i32_i24_e32 v1, 64, v1
	v_sub_u32_e32 v1, v30, v1
	v_lshrrev_b16_sdwa v2, v196, sext(v1) dst_sel:DWORD dst_unused:UNUSED_PAD src0_sel:DWORD src1_sel:BYTE_0
	v_and_b32_e32 v2, 3, v2
	v_add_u16_e32 v2, v1, v2
	v_ashrrev_i16_sdwa v3, v197, sext(v2) dst_sel:DWORD dst_unused:UNUSED_PAD src0_sel:DWORD src1_sel:BYTE_0
	v_and_b32_e32 v2, 0xfc, v2
	v_sub_u16_e32 v1, v1, v2
	v_and_b32_e32 v0, 0x7ffffc0, v0
	v_lshlrev_b32_sdwa v1, v198, sext(v1) dst_sel:DWORD dst_unused:UNUSED_PAD src0_sel:DWORD src1_sel:BYTE_0
	v_bfe_i32 v2, v3, 0, 16
	v_add3_u32 v41, v0, v2, v1
	v_add_u32_e32 v0, 32, v30
	v_ashrrev_i32_e32 v1, 31, v0
	v_lshrrev_b32_e32 v1, 26, v1
	v_add_u32_e32 v1, v0, v1
	v_lshrrev_b32_e32 v2, 6, v1
	v_mul_i32_i24_e32 v2, 64, v2
	v_sub_u32_e32 v0, v0, v2
	v_lshrrev_b16_sdwa v2, v196, sext(v0) dst_sel:DWORD dst_unused:UNUSED_PAD src0_sel:DWORD src1_sel:BYTE_0
	v_and_b32_e32 v2, 3, v2
	v_add_u16_e32 v2, v0, v2
	v_ashrrev_i16_sdwa v3, v197, sext(v2) dst_sel:DWORD dst_unused:UNUSED_PAD src0_sel:DWORD src1_sel:BYTE_0
	v_and_b32_e32 v2, 0xfc, v2
	v_sub_u16_e32 v0, v0, v2
	v_and_b32_e32 v1, 0x7ffffc0, v1
	v_lshlrev_b32_sdwa v0, v198, sext(v0) dst_sel:DWORD dst_unused:UNUSED_PAD src0_sel:DWORD src1_sel:BYTE_0
	v_bfe_i32 v2, v3, 0, 16
	v_add3_u32 v42, v1, v2, v0
	v_add_u32_e32 v0, 64, v30
	v_ashrrev_i32_e32 v1, 31, v0
	v_lshrrev_b32_e32 v1, 26, v1
	v_add_u32_e32 v1, v0, v1
	v_lshrrev_b32_e32 v2, 6, v1
	v_mul_i32_i24_e32 v2, 64, v2
	v_sub_u32_e32 v0, v0, v2
	v_lshrrev_b16_sdwa v2, v196, sext(v0) dst_sel:DWORD dst_unused:UNUSED_PAD src0_sel:DWORD src1_sel:BYTE_0
	v_and_b32_e32 v2, 3, v2
	v_add_u16_e32 v2, v0, v2
	v_ashrrev_i16_sdwa v3, v197, sext(v2) dst_sel:DWORD dst_unused:UNUSED_PAD src0_sel:DWORD src1_sel:BYTE_0
	v_and_b32_e32 v2, 0xfc, v2
	v_sub_u16_e32 v0, v0, v2
	v_and_b32_e32 v1, 0x7ffffc0, v1
	v_lshlrev_b32_sdwa v0, v198, sext(v0) dst_sel:DWORD dst_unused:UNUSED_PAD src0_sel:DWORD src1_sel:BYTE_0
	v_bfe_i32 v2, v3, 0, 16
	v_add3_u32 v43, v1, v2, v0
	v_add_u32_e32 v0, 0x60, v30
	v_ashrrev_i32_e32 v1, 31, v0
	v_lshrrev_b32_e32 v1, 26, v1
	v_add_u32_e32 v1, v0, v1
	v_lshrrev_b32_e32 v2, 6, v1
	v_mul_i32_i24_e32 v2, 64, v2
	v_sub_u32_e32 v0, v0, v2
	s_lshr_b32 s13, s2, 5
	v_lshrrev_b16_sdwa v2, v196, sext(v0) dst_sel:DWORD dst_unused:UNUSED_PAD src0_sel:DWORD src1_sel:BYTE_0
	s_lshl_b32 s86, s13, 17
	v_and_b32_e32 v2, 3, v2
	s_and_b32 s12, s74, 31
	s_lshl_b64 s[14:15], s[86:87], 1
	v_add_u16_e32 v2, v0, v2
	s_add_u32 s18, s80, s14
	v_ashrrev_i16_sdwa v3, v197, sext(v2) dst_sel:DWORD dst_unused:UNUSED_PAD src0_sel:DWORD src1_sel:BYTE_0
	v_and_b32_e32 v2, 0xfc, v2
	s_addc_u32 s19, s81, s15
	s_lshl_b32 s2, s12, 18
	v_sub_u16_e32 v0, v0, v2
	s_add_u32 s22, s11, s2
	v_and_b32_e32 v1, 0x7ffffc0, v1
	v_lshlrev_b32_sdwa v0, v198, sext(v0) dst_sel:DWORD dst_unused:UNUSED_PAD src0_sel:DWORD src1_sel:BYTE_0
	v_bfe_i32 v2, v3, 0, 16
	v_ashrrev_i32_e32 v31, 31, v30
	s_addc_u32 s23, s39, 0
	v_add3_u32 v44, v1, v2, v0
	v_lshlrev_b64 v[32:33], 11, v[30:31]
	v_lshlrev_b32_e32 v2, 4, v40
	v_lshl_add_u64 v[0:1], s[22:23], 0, v[32:33]
	v_and_b32_e32 v38, 0x70, v2
	v_mov_b32_e32 v39, v13
	v_lshl_add_u64 v[8:9], v[0:1], 0, v[38:39]
	v_add_co_u32_e32 v0, vcc, s7, v8
	v_mul_lo_u32 v46, v30, s89
	s_nop 0
	v_addc_co_u32_e32 v1, vcc, 0, v9, vcc
	v_add_co_u32_e32 v10, vcc, s37, v8
	v_mov_b32_e32 v250, v8
	v_mov_b32_e32 v251, v9
	s_nop 0
	v_addc_co_u32_e32 v11, vcc, 0, v9, vcc
	v_add_co_u32_e32 v14, vcc, s73, v8
	v_and_b32_e32 v30, 7, v40
	s_nop 0
	v_addc_co_u32_e32 v15, vcc, 0, v9, vcc
	s_nop 0
	v_lshl_add_u64 v[14:15], s[18:19], 0, v[32:33]
	v_lshl_add_u64 v[26:27], v[14:15], 0, v[38:39]
	v_add_co_u32_e32 v14, vcc, s7, v26
	s_add_u32 s14, s58, s14
	s_nop 0
	v_addc_co_u32_e32 v15, vcc, 0, v27, vcc
	v_add_co_u32_e32 v28, vcc, s37, v26
	v_mov_b32_e32 v248, v26
	v_mov_b32_e32 v249, v27
	s_nop 0
	v_addc_co_u32_e32 v29, vcc, 0, v27, vcc
	v_add_co_u32_e32 v34, vcc, s73, v26
	v_and_b32_e32 v31, 15, v40
	s_nop 0
	v_addc_co_u32_e32 v35, vcc, 0, v27, vcc
	s_nop 0
	v_lshrrev_b32_e32 v39, 1, v40
	v_lshl_or_b32 v32, v30, 4, v32
	s_addc_u32 s15, s59, s15
	v_and_or_b32 v31, v39, s3, v31
	v_and_b32_e32 v39, 0x4f, v40
	v_lshl_add_u64 v[98:99], s[14:15], 0, v[32:33]
	s_add_u32 s14, s58, s2
	v_and_b32_e32 v45, 48, v40
	v_mul_lo_u32 v31, v31, s89
	v_mul_u32_u24_e32 v39, 0xa0, v39
	v_mul_lo_u32 v41, v41, s89
	v_mul_lo_u32 v42, v42, s89
	v_mul_lo_u32 v43, v43, s89
	v_mul_lo_u32 v44, v44, s89
	s_addc_u32 s15, s59, 0
	v_mov_b32_e32 v30, 0
	v_lshl_add_u64 v[100:101], s[14:15], 0, v[32:33]
	s_mov_b64 s[14:15], 0
	v_add_u32_e32 v104, v38, v46
	v_add_u32_e32 v105, v38, v41
	v_add_u32_e32 v106, v38, v42
	v_add_u32_e32 v107, v38, v43
; template <int NT>
; __device__ __forceinline__ void gemm_tile(f32x4 (&acc)[4][NT], const bf16_t* A, int lda, const bf16_t* B, int ldb, int K, bf16_t* sm) {
;     ...
;     u32x4 ra0[4], rb0[NT];
; #pragma unroll
;     for (int i = 0; i < 4; ++i) ra0[i] = *(const u32x4*)(ga + (size_t)(32 * i) * lda);
; #pragma unroll
;     for (int i = 0; i < NT; ++i) rb0[i] = *(const u32x4*)(gb + (size_t)(32 * i) * ldb);
;     const int nk = K >> 6;
;     for (int kt = 0; kt < nk; ++kt) {
;         lds_barrier();
; #pragma unroll
;         for (int i = 0; i < 4; ++i) *(u32x4*)(sA + (lrow + 32 * i) * LDT + lkc * 8) = ra0[i];
; #pragma unroll
;         for (int i = 0; i < NT; ++i) *(u32x4*)(sB + sbrow[i] * LDT + lkc * 8) = rb0[i];
;         lds_barrier();
;         if (kt + 1 < nk) {
;             ga += 64; gb += 64;
; #pragma unroll
;             for (int i = 0; i < 4; ++i) ra0[i] = *(const u32x4*)(ga + (size_t)(32 * i) * lda);
; #pragma unroll
;             for (int i = 0; i < NT; ++i) rb0[i] = *(const u32x4*)(gb + (size_t)(32 * i) * ldb);
;         }
;         __builtin_amdgcn_sched_barrier(0);
;         gemm_compute<NT>(acc, sA, sB, wr, wc, fr, fq);
; template <int NT> __device__ __forceinline__ void zero_acc(f32x4 (&acc)[4][NT]) {
; #pragma unroll
;     for (int mt = 0; mt < 4; ++mt)
; #pragma unroll
;         for (int nt = 0; nt < NT; ++nt) acc[mt][nt] = (f32x4){0.f, 0.f, 0.f, 0.f};
; }
	v_add_u32_e32 v108, v38, v44
	v_add_u32_e32 v103, v45, v31
	v_add_u32_e32 v102, v45, v39
	v_mov_b32_e32 v31, v30
	v_mov_b32_e32 v32, v30
	v_mov_b32_e32 v33, v30
	v_mov_b32_e32 v38, v30
	v_mov_b32_e32 v39, v30
	v_mov_b32_e32 v40, v30
	v_mov_b32_e32 v41, v30
	v_mov_b32_e32 v42, v30
	v_mov_b32_e32 v43, v30
	v_mov_b32_e32 v44, v30
	v_mov_b32_e32 v45, v30
	v_mov_b32_e32 v46, v30
	v_mov_b32_e32 v47, v30
	v_mov_b32_e32 v48, v30
	v_mov_b32_e32 v49, v30
	v_mov_b32_e32 v50, v30
	v_mov_b32_e32 v51, v30
	v_mov_b32_e32 v52, v30
	v_mov_b32_e32 v53, v30
	v_mov_b32_e32 v54, v30
	v_mov_b32_e32 v55, v30
	v_mov_b32_e32 v56, v30
	v_mov_b32_e32 v57, v30
	v_mov_b32_e32 v58, v30
	v_mov_b32_e32 v59, v30
	v_mov_b32_e32 v60, v30
	v_mov_b32_e32 v61, v30
	v_mov_b32_e32 v62, v30
	v_mov_b32_e32 v63, v30
	v_mov_b32_e32 v64, v30
	v_mov_b32_e32 v65, v30
	v_mov_b32_e32 v66, v30
	v_mov_b32_e32 v67, v30
	v_mov_b32_e32 v68, v30
	v_mov_b32_e32 v69, v30
	v_mov_b32_e32 v70, v30
	v_mov_b32_e32 v71, v30
	v_mov_b32_e32 v72, v30
	v_mov_b32_e32 v73, v30
	v_mov_b32_e32 v74, v30
	v_mov_b32_e32 v75, v30
	v_mov_b32_e32 v76, v30
	v_mov_b32_e32 v77, v30
	v_mov_b32_e32 v78, v30
	v_mov_b32_e32 v79, v30
	v_mov_b32_e32 v80, v30
	v_mov_b32_e32 v81, v30
	v_mov_b32_e32 v82, v30
	v_mov_b32_e32 v83, v30
	v_mov_b32_e32 v84, v30
	v_mov_b32_e32 v85, v30
	v_mov_b32_e32 v86, v30
	v_mov_b32_e32 v87, v30
	v_mov_b32_e32 v88, v30
	v_mov_b32_e32 v89, v30
	v_mov_b32_e32 v90, v30
	v_mov_b32_e32 v91, v30
	v_mov_b32_e32 v92, v30
	v_mov_b32_e32 v93, v30
	v_mov_b32_e32 v94, v30
	v_mov_b32_e32 v95, v30
	v_mov_b32_e32 v96, v30
	v_mov_b32_e32 v97, v30
	v_writelane_b32 v234, s90, 0
	v_writelane_b32 v234, s91, 1
	v_writelane_b32 v234, s92, 2
	v_writelane_b32 v234, s93, 3
	v_writelane_b32 v234, s94, 4
	v_writelane_b32 v234, s95, 5
	v_bfe_u32 v160, v192, 3, 3
	v_and_b32_e32 v161, 7, v192
	v_xor_b32_e32 v161, v160, v161
	v_lshlrev_b32_e32 v161, 4, v161
	v_lshrrev_b32_e32 v162, 6, v192
	v_lshl_add_u32 v163, v162, 5, v160
	v_mul_u32_u24_e32 v163, 0x800, v163
	v_add_u32_e32 v236, v163, v161
	v_add_u32_e32 v237, 0x3c00, v236
	v_add_u32_e32 v238, 0x3c00, v237
	v_add_u32_e32 v239, 0x3c00, v238
	v_lshrrev_b32_e32 v163, 7, v192
	v_bfe_u32 v162, v192, 6, 1
	v_lshlrev_b32_e32 v163, 6, v163
	v_lshl_add_u32 v163, v160, 2, v163
	v_lshl_add_u32 v163, v162, 1, v163
	v_mul_u32_u24_e32 v163, 0x800, v163
	v_add_u32_e32 v240, v163, v161
	v_add_u32_e32 v241, 0xfc00, v240
	v_subrev_u32_e32 v242, 0xfc00, v241
	v_add_u32_e32 v243, 0xfc00, v242
	v_and_b32_e32 v160, 15, v192
	v_bfe_u32 v161, v192, 4, 2
	v_and_b32_e32 v162, 7, v160
	v_xor_b32_e32 v161, v161, v162
	v_lshlrev_b32_e32 v161, 4, v161
	v_lshl_add_u32 v161, v160, 7, v161
	v_lshrrev_b32_e32 v162, 7, v192
	v_lshl_add_u32 v244, v162, 13, v161
	v_bfe_u32 v162, v192, 6, 1
	v_lshl_add_u32 v246, v162, 13, v161
	v_add_u32_e32 v246, 0x4000, v246
	v_xor_b32_e32 v245, 64, v244
	v_xor_b32_e32 v247, 64, v246
	v_lshrrev_b32_e32 v160, 6, v192
	s_nop 0
	v_readfirstlane_b32 s94, v160
	v_readfirstlane_b32 s90, v248
	v_readfirstlane_b32 s91, v249
	v_readfirstlane_b32 s92, v250
	v_readfirstlane_b32 s93, v251
	s_mul_i32 s95, s94, 0x4000
	s_sub_u32 s90, s90, s95
	s_subb_u32 s91, s91, 0
	s_mul_i32 s95, s94, 0x4000
	s_sub_u32 s92, s92, s95
	s_subb_u32 s93, s93, 0
	s_lshl_b32 s94, s94, 10
	s_waitcnt lgkmcnt(0)
	s_barrier
	s_lshl_b32 s95, s94, 2
	s_add_u32 m0, s95, 0x0
	s_nop 0
	global_load_lds_dwordx4 v236, s[90:91]
	global_load_lds_dwordx4 v237, s[90:91] offset:1024
	global_load_lds_dwordx4 v238, s[90:91] offset:2048
	global_load_lds_dwordx4 v239, s[90:91] offset:3072
	s_mul_i32 s95, s94, 4
	s_add_u32 m0, s95, 0x4000
	s_nop 0
	global_load_lds_dwordx4 v240, s[92:93]
	global_load_lds_dwordx4 v241, s[92:93] offset:1024
	global_load_lds_dwordx4 v242, s[92:93] offset:2048
	global_load_lds_dwordx4 v243, s[92:93] offset:3072
	s_add_u32 s90, s90, 0x80
	s_addc_u32 s91, s91, 0
	s_add_u32 s92, s92, 0x80
	s_addc_u32 s93, s93, 0
	s_waitcnt vmcnt(0)
	s_barrier
	s_lshl_b32 s95, s94, 2
	s_add_u32 m0, s95, 0x8000
	s_nop 0
	global_load_lds_dwordx4 v236, s[90:91]
	global_load_lds_dwordx4 v237, s[90:91] offset:1024
	global_load_lds_dwordx4 v238, s[90:91] offset:2048
	global_load_lds_dwordx4 v239, s[90:91] offset:3072
	s_mul_i32 s95, s94, 4
	s_add_u32 m0, s95, 0xc000
	s_nop 0
	global_load_lds_dwordx4 v240, s[92:93]
	global_load_lds_dwordx4 v241, s[92:93] offset:1024
	global_load_lds_dwordx4 v242, s[92:93] offset:2048
	global_load_lds_dwordx4 v243, s[92:93] offset:3072
	s_add_u32 s90, s90, 0x80
	s_addc_u32 s91, s91, 0
	s_add_u32 s92, s92, 0x80
	s_addc_u32 s93, s93, 0
	ds_read_b128 v[110:113], v244 offset:0
	ds_read_b128 v[114:117], v244 offset:2048
	ds_read_b128 v[118:121], v244 offset:4096
	ds_read_b128 v[122:125], v244 offset:6144
	ds_read_b128 v[126:129], v246 offset:0
	ds_read_b128 v[130:133], v246 offset:2048
	ds_read_b128 v[134:137], v246 offset:4096
	ds_read_b128 v[138:141], v246 offset:6144
	s_movk_i32 s95, 0x6
	s_cmp_eq_u32 s95, 0
	s_cbranch_scc1 .Lgemm_x178
	.p2align	6
